# GEMM phase prologues: second wave-row also issues K-tile 1 loads before its skew barrier
# speedup vs baseline: 1.0088x; 1.0019x over previous
.LBB0_439:
	v_ashrrev_i32_e32 v0, 31, v166
	v_lshrrev_b32_e32 v0, 26, v0
	v_add_u32_e32 v0, v166, v0
	v_ashrrev_i32_e32 v10, 6, v0
	v_bfe_i32 v0, v166, 27, 1
	v_lshlrev_b32_e32 v2, 4, v166
	v_lshrrev_b32_e32 v0, 22, v0
	v_add_u32_e32 v0, v2, v0
	v_and_b32_e32 v0, 0xfffffc00, v0
	v_sub_u32_e32 v0, v2, v0
	s_waitcnt lgkmcnt(0)
	v_lshrrev_b32_e32 v3, 4, v0
	v_bitop3_b32 v0, v3, v0, 32 bitop3:0x6c
	v_ashrrev_i32_e32 v4, 31, v0
	v_lshrrev_b32_e32 v4, 26, v4
	v_add_u32_e32 v4, v0, v4
	v_ashrrev_i32_e32 v11, 6, v4
	v_and_b32_e32 v4, 0xc0, v4
	v_sub_u32_e32 v0, v0, v4
	v_lshlrev_b32_e32 v3, 3, v10
	v_lshlrev_b32_e32 v5, 5, v10
	v_ashrrev_i16_sdwa v0, v219, sext(v0) dst_sel:DWORD dst_unused:UNUSED_PAD src0_sel:DWORD src1_sel:BYTE_0
	s_add_i32 s4, s6, s4
	v_and_b32_e32 v3, 0x1ffff0, v3
	v_and_b32_e32 v5, 32, v5
	v_bfe_i32 v12, v0, 0, 16
	s_ashr_i32 s5, s4, 31
	v_add_u32_e32 v0, v5, v12
	v_add_lshl_u32 v3, v11, v3, 11
	v_add_u32_e32 v2, 0x2000, v2
	s_lshr_b32 s5, s5, 28
	v_lshl_add_u32 v0, v0, 1, v3
	v_ashrrev_i32_e32 v3, 31, v2
	s_add_i32 s5, s4, s5
	v_lshrrev_b32_e32 v3, 22, v3
	s_ashr_i32 s6, s5, 4
	s_and_b32 s5, s5, 0xfff0
	v_add_u32_e32 v3, v2, v3
	s_sub_i32 s4, s4, s5
	v_ashrrev_i32_e32 v13, 10, v3
	s_bfe_i32 s5, s4, 0x80000
	v_mul_i32_i24_e32 v3, 0x400, v13
	s_bfe_u32 s5, s5, 0x3000c
	v_sub_u32_e32 v2, v2, v3
	s_add_i32 s5, s4, s5
	v_lshrrev_b32_e32 v3, 4, v2
	s_bfe_i32 s7, s5, 0x80000
	s_and_b32 s5, s5, 0xf8
	v_bitop3_b32 v2, v3, v2, 32 bitop3:0x6c
	s_sub_i32 s4, s4, s5
	v_ashrrev_i32_e32 v4, 31, v2
	s_lshl_b32 s6, s6, 3
	s_sext_i32_i16 s7, s7
	s_sext_i32_i8 s4, s4
	v_lshrrev_b32_e32 v4, 26, v4
	s_lshr_b32 s8, s7, 3
	s_add_i32 s6, s6, s4
	v_add_u32_e32 v4, v2, v4
	s_ashr_i32 s11, s9, 6
	s_ashr_i32 s7, s6, 31
	s_bfe_i64 s[12:13], s[8:9], 0x100000
	s_ashr_i32 s10, s9, 8
	v_ashrrev_i32_e32 v14, 6, v4
	v_and_b32_e32 v4, 0xc0, v4
	s_lshl_b32 s66, s11, 10
	s_lshl_b64 s[4:5], s[6:7], 19
	s_lshl_b64 s[12:13], s[12:13], 19
	v_sub_u32_e32 v2, v2, v4
	s_add_u32 s28, s18, s12
	v_lshlrev_b32_e32 v3, 3, v13
	v_lshlrev_b32_e32 v5, 5, v13
	v_ashrrev_i16_sdwa v2, v219, sext(v2) dst_sel:DWORD dst_unused:UNUSED_PAD src0_sel:DWORD src1_sel:BYTE_0
	s_addc_u32 s29, s19, s13
	s_add_i32 s67, s66, 0
	v_and_b32_e32 v3, 0x1ffff0, v3
	v_and_b32_e32 v5, 32, v5
	v_bfe_i32 v15, v2, 0, 16
	s_add_i32 m0, s67, 0x10000
	v_add_u32_e32 v2, v5, v15
	v_add_lshl_u32 v3, v14, v3, 11
	global_load_lds_dwordx4 v0, s[28:29]
	s_add_i32 m0, s67, 0x12000
	s_waitcnt vmcnt(0)
	v_lshl_add_u32 v130, v2, 1, v3
	s_add_u32 s12, s28, 0x40000
	global_load_lds_dwordx4 v130, s[28:29]
	s_addc_u32 s13, s29, 0
	s_add_i32 m0, s67, 0x14000
	v_writelane_b32 v254, s82, 52
	global_load_lds_dwordx4 v0, s[12:13]
	s_add_i32 m0, s67, 0x16000
	s_add_u32 s30, s2, s4
	s_addc_u32 s31, s3, s5
	s_add_i32 s68, s67, 0x2000
	global_load_lds_dwordx4 v130, s[12:13]
	s_mov_b32 m0, s67
	s_add_u32 s4, s30, 0x40000
	global_load_lds_dwordx4 v0, s[30:31]
	s_mov_b32 m0, s68
	s_addc_u32 s5, s31, 0
	s_add_i32 s70, s67, 0x4000
	global_load_lds_dwordx4 v130, s[30:31]
	s_mov_b32 m0, s70
	s_add_i32 s71, s67, 0x6000
	global_load_lds_dwordx4 v0, s[4:5]
	s_mov_b32 m0, s71
	v_mov_b32_e32 v131, v1
	global_load_lds_dwordx4 v130, s[4:5]
	s_cmp_eq_u32 s10, 1
	v_writelane_b32 v254, s83, 53
	v_lshl_add_u64 v[8:9], s[28:29], 0, v[0:1]
	v_lshl_add_u64 v[6:7], s[28:29], 0, v[130:131]
	v_lshl_add_u64 v[2:3], s[30:31], 0, v[0:1]
	s_cselect_b64 s[4:5], -1, 0
	v_lshl_add_u64 v[4:5], s[30:31], 0, v[130:131]
	s_mov_b32 s101, s10
	v_bfe_u32 v17, v166, 4, 2
	v_and_b32_e32 v16, 15, v166
	v_lshlrev_b32_e32 v18, 4, v17
	v_lshl_or_b32 v136, s10, 6, v16
	v_lshl_or_b32 v16, v16, 6, v18
	v_lshlrev_b32_e32 v18, 2, v166
	s_sext_i32_i8 s7, s8
	s_lshl_b32 s8, s10, 13
	v_and_b32_e32 v18, 32, v18
	v_bitop3_b32 v19, v16, s8, v18 bitop3:0xde
	s_lshl_b32 s8, s11, 5
	s_and_b32 s12, s8, 0x60
	s_add_i32 m0, s67, 0x18000
	v_lshl_add_u64 v[8:9], v[8:9], 0, s[22:23]
	s_lshl_b32 s8, s12, 7
	global_load_lds_dwordx4 v[8:9], off
	v_lshl_add_u64 v[6:7], v[6:7], 0, s[22:23]
	s_add_i32 m0, s67, 0x1a000
	s_add_i32 s80, s67, 0x8000
	s_add_i32 s81, s67, 0xa000
	global_load_lds_dwordx4 v[6:7], off
	v_lshl_add_u64 v[2:3], v[2:3], 0, s[22:23]
	s_mov_b32 m0, s80
	s_add_u32 s10, s28, 0x40080
	global_load_lds_dwordx4 v[2:3], off
	v_lshl_add_u64 v[2:3], v[4:5], 0, s[22:23]
	s_mov_b32 m0, s81
	s_addc_u32 s11, s29, 0
	global_load_lds_dwordx4 v[2:3], off
	s_add_i32 m0, s67, 0x1c000
	v_lshl_add_u64 v[2:3], s[10:11], 0, v[0:1]
	global_load_lds_dwordx4 v[2:3], off
	v_lshl_add_u64 v[2:3], s[10:11], 0, v[130:131]
	s_add_i32 m0, s67, 0x1e000
	s_nop 0
	global_load_lds_dwordx4 v[2:3], off
	s_cmp_lg_u32 s101, 1
	s_cbranch_scc1 .LBB0_441
	s_barrier
.LBB0_441:
	s_cmpk_lt_u32 s9, 0x100
	s_waitcnt vmcnt(8)
	s_barrier
	v_lshlrev_b32_e32 v2, 14, v13
	v_and_b32_e32 v2, 0xffff8000, v2
	v_lshl_add_u32 v2, v14, 11, v2
	v_and_b32_e32 v3, 1, v13
	v_lshl_or_b32 v2, v3, 6, v2
	v_lshl_add_u32 v132, v15, 1, v2
	v_lshlrev_b32_e32 v2, 14, v10
	v_and_b32_e32 v2, 0xffff8000, v2
	s_waitcnt vmcnt(6)
	v_lshl_add_u32 v2, v11, 11, v2
	v_and_b32_e32 v3, 1, v10
	v_lshl_or_b32 v2, v3, 6, v2
	v_bitop3_b32 v137, s8, v16, v18 bitop3:0xf6
	s_cselect_b64 s[8:9], -1, 0
	s_ashr_i32 s82, s63, 31
	v_lshl_or_b32 v138, v17, 2, s12
	v_mov_b32_e32 v133, v1
	v_lshl_add_u32 v134, v12, 1, v2
	v_mov_b32_e32 v135, v1
	s_mov_b32 s83, 0
	v_add_u32_e32 v139, 0, v19
	s_barrier
	s_branch .LBB0_444

.LBB0_583:
	s_andn2_b64 vcc, exec, s[2:3]
	s_cbranch_vccnz .LBB0_867
	v_bfe_i32 v3, v166, 27, 1
	v_lshlrev_b32_e32 v2, 4, v166
	v_lshrrev_b32_e32 v3, 22, v3
	v_add_u32_e32 v3, v2, v3
	v_and_b32_e32 v3, 0xfffffc00, v3
	v_sub_u32_e32 v3, v2, v3
	v_lshrrev_b32_e32 v4, 4, v3
	v_ashrrev_i32_e32 v0, 31, v166
	v_bitop3_b32 v3, v4, v3, 32 bitop3:0x6c
	v_lshrrev_b32_e32 v0, 26, v0
	v_ashrrev_i32_e32 v5, 31, v3
	v_add_u32_e32 v0, v166, v0
	v_lshrrev_b32_e32 v5, 26, v5
	v_ashrrev_i32_e32 v0, 6, v0
	v_add_u32_e32 v5, v3, v5
	v_lshlrev_b32_e32 v4, 3, v0
	v_ashrrev_i32_e32 v10, 6, v5
	v_and_b32_e32 v5, 0xc0, v5
	v_and_b32_e32 v4, -16, v4
	v_sub_u32_e32 v3, v3, v5
	v_add_u32_e32 v4, v10, v4
	v_ashrrev_i16_sdwa v3, v219, sext(v3) dst_sel:DWORD dst_unused:UNUSED_PAD src0_sel:DWORD src1_sel:BYTE_0
	v_lshlrev_b32_e32 v6, 5, v0
	v_bfe_i32 v11, v3, 0, 16
	v_lshlrev_b32_e32 v3, 1, v4
	v_lshrrev_b32_e32 v5, 2, v4
	v_and_b32_e32 v7, 3, v10
	s_mov_b32 s1, 0x1fffe0
	v_and_b32_e32 v6, 32, v6
	v_and_b32_e32 v3, 24, v3
	v_and_b32_e32 v5, 4, v5
	v_and_or_b32 v7, v4, s1, v7
	v_or3_b32 v3, v7, v5, v3
	v_add_lshl_u32 v5, v6, v11, 1
	v_add_u32_e32 v2, 0x2000, v2
	v_lshl_add_u32 v132, v3, 11, v5
	v_ashrrev_i32_e32 v3, 31, v2
	v_lshrrev_b32_e32 v3, 22, v3
	v_add_u32_e32 v3, v2, v3
	v_ashrrev_i32_e32 v12, 10, v3
	v_mul_i32_i24_e32 v3, 0x400, v12
	v_sub_u32_e32 v2, v2, v3
	v_lshrrev_b32_e32 v3, 4, v2
	v_bitop3_b32 v2, v3, v2, 32 bitop3:0x6c
	v_lshl_add_u32 v130, v4, 11, v5
	v_ashrrev_i32_e32 v4, 31, v2
	v_lshrrev_b32_e32 v4, 26, v4
	v_lshlrev_b32_e32 v3, 3, v12
	v_add_u32_e32 v4, v2, v4
	v_and_b32_e32 v3, -16, v3
	v_ashrrev_i32_e32 v13, 6, v4
	v_writelane_b32 v254, s78, 52
	v_add_u32_e32 v3, v13, v3
	v_and_b32_e32 v6, 3, v13
	v_writelane_b32 v254, s64, 48
	v_and_b32_e32 v4, 0xc0, v4
	v_and_or_b32 v6, v3, s1, v6
	s_ashr_i32 s3, s18, 6
	s_ashr_i32 s1, s0, 31
	s_ashr_i32 s73, s72, 31
	s_ashr_i32 s2, s18, 8
	v_sub_u32_e32 v2, v2, v4
	s_lshl_b32 s66, s3, 10
	s_lshl_b64 s[6:7], s[0:1], 19
	s_lshl_b64 s[4:5], s[72:73], 19
	v_readlane_b32 s10, v254, 39
	v_ashrrev_i16_sdwa v2, v219, sext(v2) dst_sel:DWORD dst_unused:UNUSED_PAD src0_sel:DWORD src1_sel:BYTE_0
	v_readlane_b32 s11, v254, 40
	s_add_u32 s4, s10, s4
	v_lshlrev_b32_e32 v5, 5, v12
	v_bfe_i32 v14, v2, 0, 16
	v_lshlrev_b32_e32 v2, 1, v3
	v_lshrrev_b32_e32 v4, 2, v3
	s_addc_u32 s5, s11, s5
	s_add_i32 s67, s66, 0
	v_and_b32_e32 v5, 32, v5
	v_and_b32_e32 v2, 24, v2
	v_and_b32_e32 v4, 4, v4
	s_add_i32 m0, s67, 0x10000
	v_or3_b32 v2, v6, v4, v2
	v_add_lshl_u32 v4, v5, v14, 1
	global_load_lds_dwordx4 v132, s[4:5]
	s_add_i32 m0, s67, 0x12000
	v_lshl_add_u32 v136, v2, 11, v4
	s_add_u32 s16, s4, 0x40000
	global_load_lds_dwordx4 v136, s[4:5]
	s_addc_u32 s17, s5, 0
	s_add_i32 m0, s67, 0x14000
	v_readlane_b32 s10, v254, 21
	global_load_lds_dwordx4 v132, s[16:17]
	s_add_i32 m0, s67, 0x16000
	v_readlane_b32 s11, v254, 22
	s_add_u32 s24, s10, s6
	s_addc_u32 s25, s11, s7
	s_add_i32 s73, s67, 0x2000
	global_load_lds_dwordx4 v136, s[16:17]
	s_mov_b32 m0, s67
	s_add_u32 s6, s24, 0x40000
	v_lshl_add_u32 v134, v3, 11, v4
	global_load_lds_dwordx4 v130, s[24:25]
	s_mov_b32 m0, s73
	s_addc_u32 s7, s25, 0
	s_add_i32 s20, s67, 0x4000
	global_load_lds_dwordx4 v134, s[24:25]
	s_mov_b32 m0, s20
	s_add_i32 s21, s67, 0x6000
	global_load_lds_dwordx4 v130, s[6:7]
	s_mov_b32 m0, s21
	s_cmp_eq_u32 s2, 1
	global_load_lds_dwordx4 v134, s[6:7]
	s_cselect_b64 s[6:7], -1, 0
	v_mov_b32_e32 v133, v1
	v_mov_b32_e32 v137, v1
	v_mov_b32_e32 v131, v1
	v_mov_b32_e32 v135, v1
	v_writelane_b32 v254, s6, 50
	v_lshl_add_u64 v[6:7], s[4:5], 0, v[132:133]
	v_lshl_add_u64 v[4:5], s[4:5], 0, v[136:137]
	v_lshl_add_u64 v[2:3], s[24:25], 0, v[130:131]
	v_writelane_b32 v254, s7, 51
	v_lshl_add_u64 v[8:9], s[24:25], 0, v[134:135]
	s_mov_b32 s101, s2
	s_add_u32 s6, s58, 0x28100000
	s_addc_u32 s7, s59, 0
	v_and_b32_e32 v167, 15, v166
	s_lshl_b32 s1, s2, 6
	v_lshrrev_b32_e32 v15, 1, v166
	v_writelane_b32 v254, s6, 42
	v_or_b32_e32 v188, s1, v167
	v_and_b32_e32 v15, 24, v15
	v_writelane_b32 v254, s7, 43
	v_lshlrev_b32_e32 v16, 1, v15
	v_lshlrev_b32_e32 v17, 2, v188
	v_writelane_b32 v254, s1, 41
	v_lshl_or_b32 v16, v167, 6, v16
	s_lshl_b32 s1, s2, 13
	v_and_b32_e32 v18, 32, v17
	v_bitop3_b32 v18, v16, s1, v18 bitop3:0xde
	s_lshl_b32 s1, s3, 5
	s_and_b32 s1, s1, 0x60
	s_lshl_b32 s2, s1, 7
	s_add_u32 s16, s58, s8
	v_lshlrev_b32_e32 v19, 2, v166
	s_addc_u32 s17, s59, s9
	s_add_i32 m0, s67, 0x18000
	v_lshl_add_u64 v[6:7], v[6:7], 0, s[22:23]
	v_and_b32_e32 v19, 32, v19
	global_load_lds_dwordx4 v[6:7], off
	v_lshl_add_u64 v[4:5], v[4:5], 0, s[22:23]
	s_add_i32 m0, s67, 0x1a000
	s_add_i32 s6, s67, 0x8000
	s_add_i32 s7, s67, 0xa000
	v_bitop3_b32 v189, s2, v16, v19 bitop3:0xf6
	global_load_lds_dwordx4 v[4:5], off
	v_lshl_add_u64 v[2:3], v[2:3], 0, s[22:23]
	s_mov_b32 m0, s6
	s_add_u32 s2, s4, 0x40080
	global_load_lds_dwordx4 v[2:3], off
	v_lshl_add_u64 v[2:3], v[8:9], 0, s[22:23]
	s_mov_b32 m0, s7
	s_addc_u32 s3, s5, 0
	global_load_lds_dwordx4 v[2:3], off
	s_add_i32 m0, s67, 0x1c000
	v_lshl_add_u64 v[2:3], s[2:3], 0, v[132:133]
	global_load_lds_dwordx4 v[2:3], off
	v_lshl_add_u64 v[2:3], s[2:3], 0, v[136:137]
	s_add_i32 m0, s67, 0x1e000
	s_nop 0
	global_load_lds_dwordx4 v[2:3], off
	s_cmp_lg_u32 s101, 1
	s_cbranch_scc1 .LBB0_586
	s_barrier
.LBB0_586:
	s_cmpk_lt_u32 s18, 0x100
	s_waitcnt vmcnt(8)
	s_barrier
	v_lshlrev_b32_e32 v2, 14, v12
	v_and_b32_e32 v2, 0xffff8000, v2
	v_lshl_add_u32 v2, v13, 11, v2
	v_and_b32_e32 v3, 1, v12
	v_lshl_or_b32 v2, v3, 6, v2
	s_cselect_b64 s[2:3], -1, 0
	v_lshl_add_u32 v138, v14, 1, v2
	v_lshlrev_b32_e32 v2, 14, v0
	v_writelane_b32 v254, s2, 44
	v_subrev_co_u32_e32 v191, vcc, 13, v167
	v_and_b32_e32 v2, 0xffff8000, v2
	s_waitcnt vmcnt(6)
	v_writelane_b32 v254, s3, 45
	s_or_b64 s[2:3], s[38:39], vcc
	v_lshl_add_u32 v2, v10, 11, v2
	v_and_b32_e32 v0, 1, v0
	v_or_b32_e32 v190, s1, v15
	v_writelane_b32 v254, s2, 46
	s_add_i32 s1, 0, 0x20000
	v_lshl_or_b32 v0, v0, 6, v2
	v_writelane_b32 v254, s3, 47
	v_add_u32_e32 v192, s1, v17
	v_mov_b32_e32 v139, v1
	v_lshl_add_u32 v140, v11, 1, v0
	v_mov_b32_e32 v141, v1
	s_mov_b32 s19, 0
	v_add_u32_e32 v193, 0, v18
	s_mov_b32 s18, 0
	s_barrier
	s_branch .LBB0_589

.LBB0_882:
	s_andn2_b64 vcc, exec, s[0:1]
	s_cbranch_vccnz .LBB0_923
	v_ashrrev_i32_e32 v0, 31, v166
	v_lshrrev_b32_e32 v0, 26, v0
	v_add_u32_e32 v0, v166, v0
	v_ashrrev_i32_e32 v10, 6, v0
	v_bfe_i32 v0, v166, 27, 1
	v_lshlrev_b32_e32 v2, 4, v166
	v_lshrrev_b32_e32 v0, 22, v0
	v_add_u32_e32 v0, v2, v0
	v_and_b32_e32 v0, 0xfffffc00, v0
	v_sub_u32_e32 v0, v2, v0
	s_waitcnt lgkmcnt(0)
	v_lshrrev_b32_e32 v3, 4, v0
	v_bitop3_b32 v0, v3, v0, 32 bitop3:0x6c
	v_ashrrev_i32_e32 v4, 31, v0
	v_lshrrev_b32_e32 v4, 26, v4
	v_lshlrev_b32_e32 v3, 3, v10
	v_add_u32_e32 v4, v0, v4
	v_and_b32_e32 v3, -16, v3
	v_ashrrev_i32_e32 v12, 6, v4
	v_and_b32_e32 v4, 0xc0, v4
	v_add_u32_e32 v3, v12, v3
	v_lshlrev_b32_e32 v5, 5, v10
	v_sub_u32_e32 v0, v0, v4
	v_and_b32_e32 v11, 32, v5
	v_ashrrev_i16_sdwa v0, v219, sext(v0) dst_sel:DWORD dst_unused:UNUSED_PAD src0_sel:DWORD src1_sel:BYTE_0
	v_lshlrev_b32_e32 v4, 1, v3
	v_lshrrev_b32_e32 v5, 2, v3
	v_and_b32_e32 v6, 3, v12
	s_mov_b32 s1, 0xffffe0
	v_bfe_i32 v13, v0, 0, 16
	v_and_b32_e32 v4, 24, v4
	v_and_b32_e32 v5, 4, v5
	v_and_or_b32 v6, v3, s1, v6
	s_movk_i32 s2, 0xb00
	v_add_u32_e32 v0, v11, v13
	v_or3_b32 v4, v6, v5, v4
	v_mul_lo_u32 v3, v3, s2
	s_waitcnt vmcnt(0)
	v_add_lshl_u32 v130, v0, v3, 1
	v_mul_u32_u24_e32 v3, 0xb00, v4
	v_add_u32_e32 v2, 0x2000, v2
	v_add_lshl_u32 v0, v3, v0, 1
	v_ashrrev_i32_e32 v3, 31, v2
	v_lshrrev_b32_e32 v3, 22, v3
	v_add_u32_e32 v3, v2, v3
	v_ashrrev_i32_e32 v14, 10, v3
	v_mul_i32_i24_e32 v3, 0x400, v14
	v_sub_u32_e32 v2, v2, v3
	v_lshrrev_b32_e32 v3, 4, v2
	v_bitop3_b32 v2, v3, v2, 32 bitop3:0x6c
	v_ashrrev_i32_e32 v4, 31, v2
	v_lshrrev_b32_e32 v4, 26, v4
	v_lshlrev_b32_e32 v3, 3, v14
	v_add_u32_e32 v4, v2, v4
	v_and_b32_e32 v3, -16, v3
	v_ashrrev_i32_e32 v16, 6, v4
	v_add_u32_e32 v3, v16, v3
	v_lshlrev_b32_e32 v5, 5, v14
	v_and_b32_e32 v4, 0xc0, v4
	v_and_b32_e32 v6, 3, v16
	v_and_b32_e32 v15, 32, v5
	v_sub_u32_e32 v2, v2, v4
	v_lshlrev_b32_e32 v4, 1, v3
	v_lshrrev_b32_e32 v5, 2, v3
	v_and_or_b32 v6, v3, s1, v6
	v_mul_lo_u32 v3, v3, s2
	v_readlane_b32 s2, v254, 11
	s_ashr_i32 s0, s4, 6
	v_readlane_b32 s3, v254, 12
	s_mov_b32 s6, s2
	s_ashr_i32 s1, s4, 8
	s_lshl_b32 s18, s0, 10
	s_mul_i32 s3, s6, 0x580000
	s_mul_hi_u32 s2, s2, 0x580000
	s_add_u32 s3, s58, s3
	s_addc_u32 s2, s59, s2
	s_add_u32 s19, s3, 0x5900000
	s_addc_u32 s30, s2, 0
	s_mul_i32 s3, s69, 0x160000
	v_ashrrev_i16_sdwa v2, v219, sext(v2) dst_sel:DWORD dst_unused:UNUSED_PAD src0_sel:DWORD src1_sel:BYTE_0
	s_mul_hi_i32 s2, s69, 0x160000
	s_add_u32 s24, s19, s3
	v_bfe_i32 v17, v2, 0, 16
	v_and_b32_e32 v4, 24, v4
	v_and_b32_e32 v5, 4, v5
	s_addc_u32 s25, s30, s2
	s_add_i32 s31, s18, 0
	v_add_u32_e32 v2, v15, v17
	v_or3_b32 v4, v6, v5, v4
	s_add_i32 m0, s31, 0x10000
	v_add_lshl_u32 v132, v2, v3, 1
	v_mul_u32_u24_e32 v3, 0xb00, v4
	global_load_lds_dwordx4 v0, s[24:25]
	s_add_i32 m0, s31, 0x12000
	v_add_lshl_u32 v134, v3, v2, 1
	s_add_u32 s2, s24, 0xb0000
	global_load_lds_dwordx4 v134, s[24:25]
	s_addc_u32 s3, s25, 0
	s_add_i32 m0, s31, 0x14000
	s_mul_i32 s6, s70, 0x160000
	global_load_lds_dwordx4 v0, s[2:3]
	s_add_i32 m0, s31, 0x16000
	s_mul_hi_i32 s5, s70, 0x160000
	s_add_u32 s20, s74, s6
	s_addc_u32 s21, s75, s5
	s_add_i32 s34, s31, 0x2000
	global_load_lds_dwordx4 v134, s[2:3]
	s_mov_b32 m0, s31
	s_add_u32 s2, s20, 0xb0000
	global_load_lds_dwordx4 v130, s[20:21]
	s_mov_b32 m0, s34
	s_addc_u32 s3, s21, 0
	s_add_i32 s35, s31, 0x4000
	global_load_lds_dwordx4 v132, s[20:21]
	s_mov_b32 m0, s35
	s_add_i32 s38, s31, 0x6000
	global_load_lds_dwordx4 v130, s[2:3]
	s_mov_b32 m0, s38
	v_mov_b32_e32 v135, v1
	global_load_lds_dwordx4 v132, s[2:3]
	v_mov_b32_e32 v131, v1
	v_mov_b32_e32 v133, v1
	s_cmp_eq_u32 s1, 1
	s_mov_b32 s81, s78
	s_mov_b32 s78, s64
	v_lshl_add_u64 v[8:9], s[24:25], 0, v[0:1]
	v_lshl_add_u64 v[6:7], s[24:25], 0, v[134:135]
	v_lshl_add_u64 v[2:3], s[20:21], 0, v[130:131]
	s_cselect_b64 s[6:7], -1, 0
	v_lshl_add_u64 v[4:5], s[20:21], 0, v[132:133]
	s_mov_b32 s101, s1
	v_readlane_b32 s2, v254, 11
	v_readlane_b32 s3, v254, 12
	s_cmp_eq_u32 s2, 0
	s_cselect_b32 s9, s41, s15
	s_cselect_b32 s8, s40, s14
	s_lshl_b64 s[2:3], s[94:95], 21
	s_add_u32 s2, s58, s2
	v_bfe_u32 v19, v166, 4, 2
	s_addc_u32 s3, s59, s3
	v_and_b32_e32 v18, 15, v166
	v_lshlrev_b32_e32 v21, 4, v19
	s_add_u32 s10, s2, 0x28c00000
	v_lshl_or_b32 v144, s1, 6, v18
	v_lshl_or_b32 v18, v18, 6, v21
	v_lshlrev_b32_e32 v21, 2, v166
	s_addc_u32 s11, s3, 0
	s_and_b32 s57, s0, 3
	s_lshl_b32 s0, s1, 13
	v_and_b32_e32 v21, 32, v21
	s_add_i32 m0, s31, 0x18000
	v_lshl_add_u64 v[8:9], v[8:9], 0, s[22:23]
	v_bitop3_b32 v22, v18, s0, v21 bitop3:0xde
	s_lshl_b32 s0, s57, 12
	global_load_lds_dwordx4 v[8:9], off
	v_lshl_add_u64 v[6:7], v[6:7], 0, s[22:23]
	s_add_i32 m0, s31, 0x1a000
	s_add_i32 s61, s31, 0x8000
	s_add_i32 s64, s31, 0xa000
	v_bitop3_b32 v145, s0, v18, v21 bitop3:0xf6
	global_load_lds_dwordx4 v[6:7], off
	v_lshl_add_u64 v[2:3], v[2:3], 0, s[22:23]
	s_mov_b32 m0, s61
	s_add_u32 s0, s24, 0xb0080
	global_load_lds_dwordx4 v[2:3], off
	v_lshl_add_u64 v[2:3], v[4:5], 0, s[22:23]
	s_mov_b32 m0, s64
	s_addc_u32 s1, s25, 0
	global_load_lds_dwordx4 v[2:3], off
	s_add_i32 m0, s31, 0x1c000
	v_lshl_add_u64 v[2:3], s[0:1], 0, v[0:1]
	global_load_lds_dwordx4 v[2:3], off
	v_lshl_add_u64 v[2:3], s[0:1], 0, v[134:135]
	s_add_i32 m0, s31, 0x1e000
	s_movk_i32 s5, 0xb00
	global_load_lds_dwordx4 v[2:3], off
	s_cmp_lg_u32 s101, 1
	s_cbranch_scc1 .LBB0_885
	s_barrier
.LBB0_885:
	s_waitcnt vmcnt(8)
	s_barrier
	s_cmpk_lt_u32 s4, 0x100
	v_lshrrev_b32_e32 v3, 1, v14
	v_mul_lo_u32 v2, v16, s5
	s_mov_b32 s4, 0xb000
	v_mad_u64_u32 v[2:3], s[0:1], v3, s4, v[2:3]
	v_or_b32_e32 v2, v2, v15
	v_add_lshl_u32 v2, v2, v17, 1
	v_mov_b32_e32 v3, v1
	s_mov_b64 s[16:17], 0xb0080
	v_lshl_add_u64 v[136:137], v[2:3], 0, s[16:17]
	v_lshrrev_b32_e32 v3, 1, v10
	v_mul_lo_u32 v2, v12, s5
	v_mad_u64_u32 v[2:3], s[0:1], v3, s4, v[2:3]
	s_waitcnt vmcnt(6)
	v_or_b32_e32 v2, v2, v11
	v_lshlrev_b32_e32 v20, 3, v19
	v_add_lshl_u32 v2, v2, v13, 1
	v_mov_b32_e32 v3, v1
	s_mov_b32 s39, 0
	v_lshl_or_b32 v146, s57, 5, v20
	s_cselect_b64 s[12:13], -1, 0
	v_cmp_eq_u32_e64 s[2:3], 0, v19
	s_ashr_i32 s65, s63, 31
	s_ashr_i32 s66, s80, 31
	v_lshl_add_u64 v[138:139], v[2:3], 0, s[16:17]
	v_add_u32_e32 v147, 0, v22
	s_barrier
	s_branch .LBB0_889

.LBB0_951:
	s_cmpk_gt_i32 s80, 0xaff
	v_readfirstlane_b32 s3, v166
	s_waitcnt vmcnt(0) lgkmcnt(0)
	s_barrier
	s_cbranch_scc1 .LBB0_967
	v_lshlrev_b32_e32 v0, 4, v166
	v_add_u32_e32 v2, 0x2000, v0
	v_ashrrev_i32_e32 v3, 31, v2
	v_lshrrev_b32_e32 v3, 22, v3
	v_add_u32_e32 v3, v2, v3
	v_ashrrev_i32_e32 v10, 10, v3
	s_mov_b32 s0, s18
	s_ashr_i32 s5, s3, 6
	v_mul_i32_i24_e32 v3, 0x400, v10
	s_ashr_i32 s4, s3, 8
	s_lshl_b32 s18, s5, 10
	s_mov_b32 s8, s0
	s_and_b32 s0, s0, 1
	v_sub_u32_e32 v2, v2, v3
	s_add_u32 s1, s58, 0x1b800000
	v_lshrrev_b32_e32 v3, 4, v2
	s_addc_u32 s2, s59, 0
	v_bitop3_b32 v2, v3, v2, 32 bitop3:0x6c
	s_cmp_eq_u32 s0, 0
	v_readlane_b32 s6, v254, 21
	v_ashrrev_i32_e32 v3, 31, v2
	v_readlane_b32 s7, v254, 22
	s_cselect_b32 s29, s6, s1
	s_mul_i32 s1, s8, 0xb00000
	v_lshrrev_b32_e32 v3, 26, v3
	s_cselect_b32 s19, s7, s2
	s_mul_hi_u32 s0, s8, 0xb00000
	s_add_u32 s1, s58, s1
	v_add_u32_e32 v3, v2, v3
	v_lshlrev_b32_e32 v4, 3, v10
	s_addc_u32 s0, s59, s0
	v_ashrrev_i32_e32 v11, 6, v3
	v_and_b32_e32 v4, -16, v4
	s_add_u32 s30, s1, 0x100000
	v_add_u32_e32 v4, v11, v4
	s_addc_u32 s31, s0, 0
	v_and_b32_e32 v5, 3, v11
	s_mov_b32 s0, 0x1fffe0
	v_lshrrev_b32_e32 v6, 2, v4
	v_lshlrev_b32_e32 v7, 1, v4
	v_and_b32_e32 v3, 0xc0, v3
	v_and_or_b32 v5, v4, s0, v5
	v_and_b32_e32 v6, 4, v6
	v_and_b32_e32 v7, 24, v7
	v_sub_u32_e32 v2, v2, v3
	v_or3_b32 v5, v5, v6, v7
	v_lshlrev_b32_e32 v6, 5, v10
	v_ashrrev_i16_sdwa v2, v219, sext(v2) dst_sel:DWORD dst_unused:UNUSED_PAD src0_sel:DWORD src1_sel:BYTE_0
	v_and_b32_e32 v6, 32, v6
	v_bfe_i32 v12, v2, 0, 16
	v_add_lshl_u32 v2, v6, v12, 1
	v_lshl_add_u32 v130, v5, 11, v2
	v_lshl_add_u32 v132, v4, 11, v2
	v_bfe_i32 v2, v166, 27, 1
	v_lshrrev_b32_e32 v2, 22, v2
	v_add_u32_e32 v2, v0, v2
	v_and_b32_e32 v2, 0xfffffc00, v2
	v_sub_u32_e32 v0, v0, v2
	v_lshrrev_b32_e32 v2, 4, v0
	v_ashrrev_i32_e32 v3, 31, v166
	v_bitop3_b32 v0, v2, v0, 32 bitop3:0x6c
	v_lshrrev_b32_e32 v3, 26, v3
	v_ashrrev_i32_e32 v2, 31, v0
	v_add_u32_e32 v3, v166, v3
	v_lshrrev_b32_e32 v2, 26, v2
	v_ashrrev_i32_e32 v14, 6, v3
	v_add_u32_e32 v2, v0, v2
	v_lshlrev_b32_e32 v3, 3, v14
	v_ashrrev_i32_e32 v13, 6, v2
	v_and_b32_e32 v3, -16, v3
	v_add_u32_e32 v3, v13, v3
	v_and_b32_e32 v4, 3, v13
	v_and_or_b32 v4, v3, s0, v4
	s_lshr_b32 s0, s81, 29
	s_add_i32 s0, s80, s0
	s_ashr_i32 s1, s0, 3
	s_and_b32 s0, s0, -8
	s_sub_i32 s0, s80, s0
	s_cmp_lt_i32 s0, 0
	s_movk_i32 s2, 0x161
	s_cselect_b32 s2, s2, 0x160
	s_mul_i32 s0, s0, s2
	s_add_i32 s0, s0, s1
	s_mul_hi_i32 s1, s0, 0x2e8ba2e9
	s_lshr_b32 s2, s1, 31
	s_ashr_i32 s1, s1, 5
	s_add_i32 s1, s1, s2
	s_lshl_b32 s6, s1, 3
	s_mulk_i32 s1, 0xb0
	s_sub_i32 s0, s0, s1
	s_bfe_u32 s1, s0, 0x3001c
	s_add_i32 s1, s0, s1
	s_sext_i32_i16 s2, s1
	s_and_b32 s1, s1, 0xfff8
	s_sub_i32 s0, s0, s1
	s_sext_i32_i16 s0, s0
	v_lshrrev_b32_e32 v5, 2, v3
	v_lshlrev_b32_e32 v6, 1, v3
	v_and_b32_e32 v2, 0xc0, v2
	s_lshr_b32 s2, s2, 3
	s_add_i32 s8, s6, s0
	v_and_b32_e32 v5, 4, v5
	v_and_b32_e32 v6, 24, v6
	v_sub_u32_e32 v0, v0, v2
	s_ashr_i32 s9, s8, 31
	s_bfe_i64 s[6:7], s[2:3], 0x100000
	v_or3_b32 v4, v4, v5, v6
	v_lshlrev_b32_e32 v5, 5, v14
	v_ashrrev_i16_sdwa v0, v219, sext(v0) dst_sel:DWORD dst_unused:UNUSED_PAD src0_sel:DWORD src1_sel:BYTE_0
	s_lshl_b64 s[0:1], s[8:9], 19
	s_lshl_b64 s[6:7], s[6:7], 19
	v_and_b32_e32 v5, 32, v5
	v_bfe_i32 v15, v0, 0, 16
	s_add_u32 s20, s30, s6
	v_add_lshl_u32 v2, v5, v15, 1
	s_addc_u32 s21, s31, s7
	s_add_i32 s34, s18, 0
	v_lshl_add_u32 v0, v4, 11, v2
	s_add_i32 m0, s34, 0x10000
	v_lshl_add_u32 v134, v3, 11, v2
	global_load_lds_dwordx4 v0, s[20:21]
	s_add_i32 m0, s34, 0x12000
	s_add_u32 s6, s20, 0x40000
	global_load_lds_dwordx4 v130, s[20:21]
	s_addc_u32 s7, s21, 0
	s_add_i32 m0, s34, 0x14000
	v_mov_b32_e32 v131, v1
	global_load_lds_dwordx4 v0, s[6:7]
	s_add_i32 m0, s34, 0x16000
	s_add_u32 s24, s29, s0
	s_addc_u32 s25, s19, s1
	s_add_i32 s35, s34, 0x2000
	global_load_lds_dwordx4 v130, s[6:7]
	s_mov_b32 m0, s34
	s_add_u32 s0, s24, 0x40000
	global_load_lds_dwordx4 v134, s[24:25]
	s_mov_b32 m0, s35
	s_addc_u32 s1, s25, 0
	s_add_i32 s38, s34, 0x4000
	global_load_lds_dwordx4 v132, s[24:25]
	s_mov_b32 m0, s38
	s_add_i32 s39, s34, 0x6000
	global_load_lds_dwordx4 v134, s[0:1]
	s_mov_b32 m0, s39
	v_mov_b32_e32 v135, v1
	global_load_lds_dwordx4 v132, s[0:1]
	v_mov_b32_e32 v133, v1
	s_cmp_eq_u32 s4, 1
	s_mov_b32 s75, s64
	v_lshl_add_u64 v[8:9], s[20:21], 0, v[0:1]
	v_lshl_add_u64 v[6:7], s[20:21], 0, v[130:131]
	v_lshl_add_u64 v[2:3], s[24:25], 0, v[134:135]
	s_cselect_b64 s[0:1], -1, 0
	v_lshl_add_u64 v[4:5], s[24:25], 0, v[132:133]
	s_mov_b32 s101, s4
	s_lshl_b32 s5, s5, 5
	s_and_b32 s11, s5, 0x60
	s_add_i32 m0, s34, 0x18000
	v_lshl_add_u64 v[8:9], v[8:9], 0, s[22:23]
	s_lshl_b32 s10, s4, 13
	s_lshl_b32 s5, s11, 7
	global_load_lds_dwordx4 v[8:9], off
	v_lshl_add_u64 v[6:7], v[6:7], 0, s[22:23]
	s_add_i32 m0, s34, 0x1a000
	s_add_i32 s57, s34, 0x8000
	s_add_i32 s61, s34, 0xa000
	global_load_lds_dwordx4 v[6:7], off
	v_lshl_add_u64 v[2:3], v[2:3], 0, s[22:23]
	s_mov_b32 m0, s57
	s_add_u32 s6, s20, 0x40080
	global_load_lds_dwordx4 v[2:3], off
	v_lshl_add_u64 v[2:3], v[4:5], 0, s[22:23]
	s_mov_b32 m0, s61
	s_addc_u32 s7, s21, 0
	global_load_lds_dwordx4 v[2:3], off
	s_add_i32 m0, s34, 0x1c000
	v_lshl_add_u64 v[2:3], s[6:7], 0, v[0:1]
	global_load_lds_dwordx4 v[2:3], off
	v_lshl_add_u64 v[2:3], s[6:7], 0, v[130:131]
	s_add_i32 m0, s34, 0x1e000
	v_lshlrev_b32_e32 v6, 2, v166
	global_load_lds_dwordx4 v[2:3], off
	s_cmp_lg_u32 s101, 1
	s_cbranch_scc1 .LBB0_954
	s_barrier
.LBB0_954:
	s_waitcnt vmcnt(8)
	s_barrier
	v_lshrrev_b32_e32 v3, 1, v166
	v_and_b32_e32 v2, 15, v166
	v_and_b32_e32 v3, 24, v3
	v_lshl_or_b32 v142, s4, 6, v2
	v_lshlrev_b32_e32 v4, 1, v3
	v_lshl_or_b32 v2, v2, 6, v4
	v_lshlrev_b32_e32 v4, 2, v142
	v_and_b32_e32 v5, 32, v4
	v_and_b32_e32 v6, 32, v6
	v_bitop3_b32 v5, v2, s10, v5 bitop3:0xde
	v_bitop3_b32 v143, s5, v2, v6 bitop3:0xf6
	v_lshlrev_b32_e32 v2, 14, v10
	v_and_b32_e32 v2, 0xffff8000, v2
	v_or_b32_e32 v144, s11, v3
	v_lshl_add_u32 v2, v11, 11, v2
	v_and_b32_e32 v3, 1, v10
	v_lshl_or_b32 v2, v3, 6, v2
	v_lshl_add_u32 v136, v12, 1, v2
	v_lshlrev_b32_e32 v2, 14, v14
	v_and_b32_e32 v2, 0xffff8000, v2
	s_waitcnt vmcnt(6)
	s_cmpk_lt_u32 s3, 0x100
	v_lshl_add_u32 v2, v13, 11, v2
	v_and_b32_e32 v3, 1, v14
	s_sext_i32_i16 s9, s2
	s_cselect_b64 s[4:5], -1, 0
	s_add_i32 s2, 0, 0x20000
	v_lshl_or_b32 v2, v3, 6, v2
	v_add_u32_e32 v145, s2, v4
	v_mov_b32_e32 v137, v1
	v_lshl_add_u32 v138, v15, 1, v2
	v_mov_b32_e32 v139, v1
	s_mov_b32 s66, 0
	v_add_u32_e32 v146, 0, v5
	s_mov_b32 s64, 0
	s_barrier
	s_branch .LBB0_957

.LBB0_980:
	s_andn2_b64 vcc, exec, s[2:3]
	s_cbranch_vccnz .LBB0_1016
	v_ashrrev_i32_e32 v0, 31, v166
	v_lshrrev_b32_e32 v0, 26, v0
	v_add_u32_e32 v0, v166, v0
	v_ashrrev_i32_e32 v10, 6, v0
	v_bfe_i32 v0, v166, 27, 1
	v_lshlrev_b32_e32 v2, 4, v166
	v_lshrrev_b32_e32 v0, 22, v0
	v_add_u32_e32 v0, v2, v0
	v_and_b32_e32 v0, 0xfffffc00, v0
	v_sub_u32_e32 v0, v2, v0
	s_waitcnt lgkmcnt(0)
	v_lshrrev_b32_e32 v3, 4, v0
	v_bitop3_b32 v0, v3, v0, 32 bitop3:0x6c
	v_ashrrev_i32_e32 v4, 31, v0
	v_lshrrev_b32_e32 v4, 26, v4
	v_add_u32_e32 v4, v0, v4
	v_lshlrev_b32_e32 v3, 3, v10
	v_ashrrev_i32_e32 v11, 6, v4
	v_and_b32_e32 v4, 0xc0, v4
	v_and_b32_e32 v3, -16, v3
	v_sub_u32_e32 v0, v0, v4
	v_add_u32_e32 v3, v11, v3
	v_ashrrev_i16_sdwa v0, v219, sext(v0) dst_sel:DWORD dst_unused:UNUSED_PAD src0_sel:DWORD src1_sel:BYTE_0
	v_lshlrev_b32_e32 v5, 5, v10
	v_bfe_i32 v12, v0, 0, 16
	v_lshlrev_b32_e32 v0, 1, v3
	v_lshrrev_b32_e32 v4, 2, v3
	v_and_b32_e32 v6, 3, v11
	s_mov_b32 s3, 0x1fffe0
	v_and_b32_e32 v5, 32, v5
	v_and_b32_e32 v0, 24, v0
	v_and_b32_e32 v4, 4, v4
	v_and_or_b32 v6, v3, s3, v6
	v_or3_b32 v0, v6, v4, v0
	v_add_lshl_u32 v4, v5, v12, 1
	v_add_u32_e32 v2, 0x2000, v2
	s_waitcnt vmcnt(0)
	v_lshl_add_u32 v130, v3, 11, v4
	v_ashrrev_i32_e32 v3, 31, v2
	v_lshrrev_b32_e32 v3, 22, v3
	v_add_u32_e32 v3, v2, v3
	v_ashrrev_i32_e32 v13, 10, v3
	v_mul_i32_i24_e32 v3, 0x400, v13
	v_sub_u32_e32 v2, v2, v3
	v_lshrrev_b32_e32 v3, 4, v2
	v_bitop3_b32 v2, v3, v2, 32 bitop3:0x6c
	v_lshl_add_u32 v0, v0, 11, v4
	v_ashrrev_i32_e32 v4, 31, v2
	v_lshrrev_b32_e32 v4, 26, v4
	v_lshlrev_b32_e32 v3, 3, v13
	v_add_u32_e32 v4, v2, v4
	v_and_b32_e32 v3, -16, v3
	v_ashrrev_i32_e32 v14, 6, v4
	s_ashr_i32 s2, s12, 6
	v_add_u32_e32 v3, v14, v3
	v_and_b32_e32 v4, 0xc0, v4
	v_and_b32_e32 v6, 3, v14
	s_ashr_i32 s25, s24, 31
	s_ashr_i32 s73, s72, 31
	v_sub_u32_e32 v2, v2, v4
	v_and_or_b32 v6, v3, s3, v6
	s_ashr_i32 s3, s12, 8
	s_lshl_b32 s34, s2, 10
	s_lshl_b64 s[4:5], s[24:25], 19
	s_lshl_b64 s[6:7], s[72:73], 19
	v_ashrrev_i16_sdwa v2, v219, sext(v2) dst_sel:DWORD dst_unused:UNUSED_PAD src0_sel:DWORD src1_sel:BYTE_0
	s_add_u32 s26, s0, s6
	v_lshlrev_b32_e32 v5, 5, v13
	v_bfe_i32 v15, v2, 0, 16
	v_lshlrev_b32_e32 v2, 1, v3
	v_lshrrev_b32_e32 v4, 2, v3
	s_addc_u32 s27, s1, s7
	s_add_i32 s35, s34, 0
	v_and_b32_e32 v5, 32, v5
	v_and_b32_e32 v2, 24, v2
	v_and_b32_e32 v4, 4, v4
	s_add_i32 m0, s35, 0x10000
	v_or3_b32 v2, v6, v4, v2
	v_add_lshl_u32 v4, v5, v15, 1
	global_load_lds_dwordx4 v0, s[26:27]
	s_add_i32 m0, s35, 0x12000
	v_lshl_add_u32 v134, v2, 11, v4
	s_add_u32 s6, s26, 0x40000
	global_load_lds_dwordx4 v134, s[26:27]
	s_addc_u32 s7, s27, 0
	s_add_i32 m0, s35, 0x14000
	v_lshl_add_u32 v132, v3, 11, v4
	global_load_lds_dwordx4 v0, s[6:7]
	s_add_i32 m0, s35, 0x16000
	s_mov_b32 s81, s64
	global_load_lds_dwordx4 v134, s[6:7]
	v_readlane_b32 s6, v254, 21
	v_readlane_b32 s7, v254, 22
	s_add_u32 s28, s6, s4
	s_addc_u32 s29, s7, s5
	s_add_i32 s57, s35, 0x2000
	s_mov_b32 m0, s35
	s_add_u32 s4, s28, 0x40000
	global_load_lds_dwordx4 v130, s[28:29]
	s_mov_b32 m0, s57
	s_addc_u32 s5, s29, 0
	s_add_i32 s61, s35, 0x4000
	global_load_lds_dwordx4 v132, s[28:29]
	s_mov_b32 m0, s61
	s_add_i32 s64, s35, 0x6000
	global_load_lds_dwordx4 v130, s[4:5]
	s_mov_b32 m0, s64
	v_mov_b32_e32 v135, v1
	global_load_lds_dwordx4 v132, s[4:5]
	v_mov_b32_e32 v131, v1
	v_mov_b32_e32 v133, v1
	s_cmp_eq_u32 s3, 1
	v_lshl_add_u64 v[8:9], s[26:27], 0, v[0:1]
	v_lshl_add_u64 v[6:7], s[26:27], 0, v[134:135]
	v_lshl_add_u64 v[2:3], s[28:29], 0, v[130:131]
	s_cselect_b64 s[6:7], -1, 0
	v_lshl_add_u64 v[4:5], s[28:29], 0, v[132:133]
	s_mov_b32 s101, s3
	s_add_u32 s8, s58, 0x1b800000
	s_addc_u32 s9, s59, 0
	s_lshl_b32 s4, s16, 22
	s_bitset1_b32 s4, 21
	s_add_u32 s4, s58, s4
	v_bfe_u32 v17, v166, 4, 2
	s_addc_u32 s5, s59, 0
	v_and_b32_e32 v16, 15, v166
	v_lshlrev_b32_e32 v19, 4, v17
	s_add_u32 s10, s4, 0x28c00000
	v_lshl_or_b32 v144, s3, 6, v16
	v_lshl_or_b32 v16, v16, 6, v19
	v_lshlrev_b32_e32 v19, 2, v166
	s_addc_u32 s11, s5, 0
	s_and_b32 s65, s2, 3
	s_lshl_b32 s2, s3, 13
	v_and_b32_e32 v19, 32, v19
	s_add_i32 m0, s35, 0x18000
	v_lshl_add_u64 v[8:9], v[8:9], 0, s[22:23]
	v_bitop3_b32 v20, v16, s2, v19 bitop3:0xde
	s_lshl_b32 s2, s65, 12
	global_load_lds_dwordx4 v[8:9], off
	v_lshl_add_u64 v[6:7], v[6:7], 0, s[22:23]
	s_add_i32 m0, s35, 0x1a000
	s_add_i32 s66, s35, 0x8000
	s_add_i32 s67, s35, 0xa000
	v_bitop3_b32 v145, s2, v16, v19 bitop3:0xf6
	global_load_lds_dwordx4 v[6:7], off
	v_lshl_add_u64 v[2:3], v[2:3], 0, s[22:23]
	s_mov_b32 m0, s66
	s_add_u32 s2, s26, 0x40080
	global_load_lds_dwordx4 v[2:3], off
	v_lshl_add_u64 v[2:3], v[4:5], 0, s[22:23]
	s_mov_b32 m0, s67
	s_addc_u32 s3, s27, 0
	global_load_lds_dwordx4 v[2:3], off
	s_add_i32 m0, s35, 0x1c000
	v_lshl_add_u64 v[2:3], s[2:3], 0, v[0:1]
	global_load_lds_dwordx4 v[2:3], off
	v_lshl_add_u64 v[2:3], s[2:3], 0, v[134:135]
	s_add_i32 m0, s35, 0x1e000
	v_lshlrev_b32_e32 v18, 3, v17
	global_load_lds_dwordx4 v[2:3], off
	s_cmp_lg_u32 s101, 1
	s_cbranch_scc1 .LBB0_983
	s_barrier
.LBB0_983:
	s_waitcnt vmcnt(8)
	s_barrier
	v_lshlrev_b32_e32 v2, 14, v13
	v_and_b32_e32 v2, 0xffff8000, v2
	v_lshl_add_u32 v2, v14, 11, v2
	v_and_b32_e32 v3, 1, v13
	v_lshl_or_b32 v2, v3, 6, v2
	v_lshl_add_u32 v136, v15, 1, v2
	v_lshlrev_b32_e32 v2, 14, v10
	v_and_b32_e32 v2, 0xffff8000, v2
	s_waitcnt vmcnt(6)
	v_lshl_add_u32 v2, v11, 11, v2
	v_and_b32_e32 v3, 1, v10
	s_cmpk_lt_u32 s12, 0x100
	v_lshl_or_b32 v2, v3, 6, v2
	v_lshl_or_b32 v146, s65, 5, v18
	s_cselect_b64 s[12:13], -1, 0
	s_mov_b32 s68, 0
	v_cmp_eq_u32_e64 s[2:3], 0, v17
	s_ashr_i32 s69, s63, 31
	s_ashr_i32 s70, s80, 31
	v_mov_b32_e32 v137, v1
	v_lshl_add_u32 v138, v12, 1, v2
	v_mov_b32_e32 v139, v1
	v_add_u32_e32 v147, 0, v20
	s_barrier
	s_branch .LBB0_986
